# grid barrier: non-leader WGs spin on the top generation word directly (no per-XCD relay); leader XGEN add removed
# baseline (speedup 1.0000x reference)
.LBB0_353:
	s_or_b64 exec, exec, s[20:21]
	v_cvt_f32_u32_e32 v5, v3
	s_waitcnt vmcnt(0)
	v_readfirstlane_b32 s4, v4
	v_sub_u32_e32 v4, 0, v3
	v_rcp_iflag_f32_e32 v5, v5
	v_add_u32_e32 v6, s4, v0
	v_mul_f32_e32 v5, 0x4f7ffffe, v5
	v_cvt_u32_f32_e32 v5, v5
	v_mul_lo_u32 v0, v4, v5
	v_mul_hi_u32 v0, v5, v0
	v_add_u32_e32 v0, v5, v0
	v_mul_hi_u32 v0, v6, v0
	v_mul_lo_u32 v4, v0, v3
	v_sub_u32_e32 v4, v6, v4
	v_add_u32_e32 v5, 1, v0
	v_cmp_ge_u32_e32 vcc, v4, v3
	s_nop 1
	v_cndmask_b32_e32 v0, v0, v5, vcc
	v_sub_u32_e32 v5, v4, v3
	v_cndmask_b32_e32 v4, v4, v5, vcc
	v_add_u32_e32 v5, 1, v0
	v_cmp_ge_u32_e32 vcc, v4, v3
	v_add_u32_e32 v4, 1, v6
	s_nop 0
	v_cndmask_b32_e32 v0, v0, v5, vcc
	v_mul_lo_u32 v5, v3, v0
	v_add_u32_e32 v3, v5, v3
	v_cmp_ne_u32_e32 vcc, v4, v3
	s_and_saveexec_b64 s[4:5], vcc
	s_xor_b64 s[20:21], exec, s[4:5]
	s_cbranch_execz .LBB0_368
	v_readlane_b32 s4, v254, 48
	v_readlane_b32 s5, v254, 49
	s_waitcnt lgkmcnt(0)
	s_nop 3
	global_load_dword v2, v1, s[4:5] sc1
	s_waitcnt vmcnt(0)
	v_cmp_eq_u32_e32 vcc, v2, v0
	s_and_saveexec_b64 s[22:23], vcc
	s_cbranch_execz .LBB0_367
	s_mov_b32 s4, 1
	s_mov_b64 s[24:25], 0
	s_branch .LBB0_357

.LBB0_385:
	s_or_b64 exec, exec, s[20:21]
	s_mov_b64 s[20:21], exec
	v_mbcnt_lo_u32_b32 v0, s20, 0
	v_mbcnt_hi_u32_b32 v0, s21, v0
	v_cmp_eq_u32_e32 vcc, 0, v0
	s_waitcnt vmcnt(0)
	buffer_inv sc1
	s_and_saveexec_b64 s[22:23], vcc
	s_cbranch_execz .LBB0_387
	s_bcnt1_i32_b64 s4, s[20:21]
	v_mov_b32_e32 v0, s4
	v_readlane_b32 s4, v254, 44
	v_readlane_b32 s5, v254, 45
	s_nop 4
.LBB0_387:
	s_or_b64 exec, exec, s[22:23]
	s_waitcnt vmcnt(0)
